# early-invalidate barrier plus write-through (sc1) on the 16-byte attention and MLA-GEMM output stores
# baseline (speedup 1.0000x reference)
.LBB0_308:
	v_readlane_b32 s2, v251, 52
	v_lshlrev_b64 v[46:47], 11, v[84:85]
	v_readlane_b32 s3, v251, 53
	v_pk_mul_f32 v[22:23], v[22:23], v[44:45]
	v_pk_mul_f32 v[24:25], v[24:25], v[44:45]
	v_pk_mul_f32 v[26:27], v[26:27], v[44:45]
	v_pk_mul_f32 v[28:29], v[28:29], v[44:45]
	v_pk_mul_f32 v[30:31], v[30:31], v[44:45]
	v_pk_mul_f32 v[32:33], v[32:33], v[44:45]
	v_pk_mul_f32 v[34:35], v[34:35], v[44:45]
	v_pk_mul_f32 v[6:7], v[6:7], v[44:45]
	v_pk_mul_f32 v[8:9], v[8:9], v[44:45]
	v_pk_mul_f32 v[10:11], v[10:11], v[44:45]
	v_pk_mul_f32 v[12:13], v[12:13], v[44:45]
	v_pk_mul_f32 v[14:15], v[14:15], v[44:45]
	v_pk_mul_f32 v[16:17], v[16:17], v[44:45]
	v_pk_mul_f32 v[18:19], v[18:19], v[44:45]
	v_lshl_add_u64 v[46:47], s[2:3], 0, v[46:47]
	v_cvt_pk_bf16_f32 v48, v40, v41
	v_cvt_pk_bf16_f32 v49, v22, v23
	v_cvt_pk_bf16_f32 v50, v24, v25
	v_cvt_pk_bf16_f32 v51, v26, v27
	v_cvt_pk_bf16_f32 v52, v28, v29
	v_cvt_pk_bf16_f32 v53, v30, v31
	v_cvt_pk_bf16_f32 v54, v32, v33
	v_cvt_pk_bf16_f32 v55, v34, v35
	v_cvt_pk_bf16_f32 v56, v36, v37
	v_cvt_pk_bf16_f32 v57, v6, v7
	v_cvt_pk_bf16_f32 v58, v8, v9
	v_cvt_pk_bf16_f32 v59, v10, v11
	v_cvt_pk_bf16_f32 v60, v12, v13
	v_cvt_pk_bf16_f32 v61, v14, v15
	v_cvt_pk_bf16_f32 v62, v16, v17
	v_cvt_pk_bf16_f32 v63, v18, v19
	v_lshl_add_u64 v[46:47], v[2:3], 2, v[46:47]
	s_nop 1
	v_permlane32_swap_b32 v48, v50
	v_permlane32_swap_b32 v49, v51
	v_permlane32_swap_b32 v52, v54
	v_permlane32_swap_b32 v53, v55
	v_permlane32_swap_b32 v56, v58
	v_permlane32_swap_b32 v57, v59
	v_permlane32_swap_b32 v60, v62
	v_permlane32_swap_b32 v61, v63
	s_nop 1
	global_store_dwordx4 v[46:47], v[48:51], off sc1
	global_store_dwordx4 v[46:47], v[52:55], off offset:32 sc1
	global_store_dwordx4 v[46:47], v[56:59], off offset:64 sc1
	global_store_dwordx4 v[46:47], v[60:63], off offset:96 sc1

.LBB0_386:
	v_xor_b32_e32 v2, 32, v229
	v_cmp_lt_i32_e32 vcc, v2, v231
	v_mov_b32_e32 v99, v3
	s_waitcnt vmcnt(0) lgkmcnt(0)
	v_cndmask_b32_e32 v2, v229, v2, vcc
	v_lshlrev_b32_e32 v2, 2, v2
	ds_bpermute_b32 v2, v2, v36
	s_barrier
	s_waitcnt lgkmcnt(0)
	s_mov_b64 s[28:29], 0
	v_add_f32_e32 v2, v36, v2
	v_div_scale_f32 v36, s[2:3], v2, v2, 1.0
	v_rcp_f32_e32 v37, v36
	v_div_scale_f32 v38, vcc, 1.0, v2, 1.0
	v_readlane_b32 s2, v251, 52
	v_fma_f32 v39, -v36, v37, 1.0
	v_fmac_f32_e32 v37, v39, v37
	v_mul_f32_e32 v39, v38, v37
	v_fma_f32 v40, -v36, v39, v38
	v_fmac_f32_e32 v39, v40, v37
	v_fma_f32 v36, -v36, v39, v38
	v_div_fmas_f32 v36, v36, v37, v39
	v_div_fixup_f32 v2, v36, v2, 1.0
	v_lshlrev_b64 v[36:37], 11, v[92:93]
	v_readlane_b32 s3, v251, 53
	v_pk_mul_f32 v[4:5], v[4:5], v[2:3] op_sel_hi:[1,0]
	v_pk_mul_f32 v[6:7], v[6:7], v[2:3] op_sel_hi:[1,0]
	v_pk_mul_f32 v[8:9], v[8:9], v[2:3] op_sel_hi:[1,0]
	v_pk_mul_f32 v[10:11], v[10:11], v[2:3] op_sel_hi:[1,0]
	v_pk_mul_f32 v[12:13], v[12:13], v[2:3] op_sel_hi:[1,0]
	v_pk_mul_f32 v[14:15], v[14:15], v[2:3] op_sel_hi:[1,0]
	v_pk_mul_f32 v[16:17], v[16:17], v[2:3] op_sel_hi:[1,0]
	v_pk_mul_f32 v[18:19], v[18:19], v[2:3] op_sel_hi:[1,0]
	v_pk_mul_f32 v[20:21], v[20:21], v[2:3] op_sel_hi:[1,0]
	v_pk_mul_f32 v[22:23], v[22:23], v[2:3] op_sel_hi:[1,0]
	v_pk_mul_f32 v[24:25], v[24:25], v[2:3] op_sel_hi:[1,0]
	v_pk_mul_f32 v[26:27], v[26:27], v[2:3] op_sel_hi:[1,0]
	v_pk_mul_f32 v[28:29], v[28:29], v[2:3] op_sel_hi:[1,0]
	v_pk_mul_f32 v[30:31], v[30:31], v[2:3] op_sel_hi:[1,0]
	v_pk_mul_f32 v[32:33], v[32:33], v[2:3] op_sel_hi:[1,0]
	v_pk_mul_f32 v[34:35], v[34:35], v[2:3] op_sel_hi:[1,0]
	v_lshl_add_u64 v[36:37], s[2:3], 0, v[36:37]
	v_cvt_pk_bf16_f32 v40, v20, v21
	v_cvt_pk_bf16_f32 v41, v22, v23
	v_cvt_pk_bf16_f32 v42, v24, v25
	v_cvt_pk_bf16_f32 v43, v26, v27
	v_cvt_pk_bf16_f32 v44, v28, v29
	v_cvt_pk_bf16_f32 v45, v30, v31
	v_cvt_pk_bf16_f32 v46, v32, v33
	v_cvt_pk_bf16_f32 v47, v34, v35
	v_cvt_pk_bf16_f32 v48, v4, v5
	v_cvt_pk_bf16_f32 v49, v6, v7
	v_cvt_pk_bf16_f32 v50, v8, v9
	v_cvt_pk_bf16_f32 v51, v10, v11
	v_cvt_pk_bf16_f32 v52, v12, v13
	v_cvt_pk_bf16_f32 v53, v14, v15
	v_cvt_pk_bf16_f32 v54, v16, v17
	v_cvt_pk_bf16_f32 v55, v18, v19
	v_lshl_add_u64 v[36:37], v[98:99], 1, v[36:37]
	s_nop 1
	v_permlane32_swap_b32 v40, v42
	v_permlane32_swap_b32 v41, v43
	v_permlane32_swap_b32 v44, v46
	v_permlane32_swap_b32 v45, v47
	v_permlane32_swap_b32 v48, v50
	v_permlane32_swap_b32 v49, v51
	v_permlane32_swap_b32 v52, v54
	v_permlane32_swap_b32 v53, v55
	s_nop 1
	global_store_dwordx4 v[36:37], v[40:43], off sc1
	global_store_dwordx4 v[36:37], v[44:47], off offset:32 sc1
	global_store_dwordx4 v[36:37], v[48:51], off offset:64 sc1
	global_store_dwordx4 v[36:37], v[52:55], off offset:96 sc1
	s_barrier

.LBB0_489:
	v_xor_b32_e32 v36, 32, v229
	v_cmp_lt_i32_e32 vcc, v36, v231
	s_waitcnt vmcnt(0) lgkmcnt(0)
	s_barrier
	v_cndmask_b32_e32 v36, v229, v36, vcc
	v_lshlrev_b32_e32 v36, 2, v36
	ds_bpermute_b32 v36, v36, v116
	s_waitcnt lgkmcnt(0)
	v_add_f32_e32 v95, v116, v36
	v_div_scale_f32 v36, s[2:3], v95, v95, 1.0
	v_rcp_f32_e32 v37, v36
	v_div_scale_f32 v38, vcc, 1.0, v95, 1.0
	v_readlane_b32 s2, v251, 56
	v_fma_f32 v39, -v36, v37, 1.0
	v_fmac_f32_e32 v37, v39, v37
	v_mul_f32_e32 v39, v38, v37
	v_fma_f32 v40, -v36, v39, v38
	v_fmac_f32_e32 v39, v40, v37
	v_fma_f32 v36, -v36, v39, v38
	v_div_fmas_f32 v36, v36, v37, v39
	v_div_fixup_f32 v44, v36, v95, 1.0
	v_readlane_b32 s3, v251, 57
	v_mov_b32_e32 v45, v44
	s_cmp_lg_u64 s[2:3], 0
	v_pk_mul_f32 v[40:41], v[20:21], v[44:45] op_sel_hi:[1,0]
	v_pk_mul_f32 v[36:37], v[4:5], v[44:45]
	s_cbranch_scc0 .LBB0_493
	v_lshlrev_b64 v[4:5], 8, v[84:85]
	v_lshl_add_u64 v[4:5], s[2:3], 0, v[4:5]
	v_lshl_add_u64 v[4:5], v[2:3], 2, v[4:5]
	v_pk_mul_f32 v[46:47], v[24:25], v[44:45]
	v_pk_mul_f32 v[48:49], v[26:27], v[44:45]
	global_store_dwordx4 v[4:5], v[46:49], off offset:32 sc1
	v_pk_mul_f32 v[42:43], v[22:23], v[44:45]
	v_pk_mul_f32 v[38:39], v[6:7], v[44:45]
	v_pk_mul_f32 v[46:47], v[28:29], v[44:45]
	v_pk_mul_f32 v[48:49], v[30:31], v[44:45]
	global_store_dwordx4 v[4:5], v[46:49], off offset:64 sc1
	v_cmp_gt_u32_e32 vcc, 32, v96
	global_store_dwordx4 v[4:5], v[40:43], off sc1
	v_pk_mul_f32 v[46:47], v[32:33], v[44:45]
	v_pk_mul_f32 v[48:49], v[34:35], v[44:45]
	global_store_dwordx4 v[4:5], v[46:49], off offset:96 sc1
	global_store_dwordx4 v[4:5], v[36:39], off offset:128 sc1
	s_nop 0
	v_pk_mul_f32 v[46:47], v[8:9], v[44:45]
	v_pk_mul_f32 v[48:49], v[10:11], v[44:45]
	global_store_dwordx4 v[4:5], v[46:49], off offset:160 sc1
	s_nop 1
	v_pk_mul_f32 v[46:47], v[12:13], v[44:45]
	v_pk_mul_f32 v[48:49], v[14:15], v[44:45]
	global_store_dwordx4 v[4:5], v[46:49], off offset:192 sc1
	s_nop 1
	v_pk_mul_f32 v[46:47], v[16:17], v[44:45]
	v_pk_mul_f32 v[48:49], v[18:19], v[44:45]
	global_store_dwordx4 v[4:5], v[46:49], off offset:224 sc1
	s_and_saveexec_b64 s[2:3], vcc
	s_cbranch_execz .LBB0_492
	v_readlane_b32 s4, v251, 54
	v_readlane_b32 s5, v251, 55
	s_nop 1
	v_lshl_add_u64 v[4:5], v[84:85], 3, s[4:5]
	global_store_dwordx2 v[4:5], v[94:95], off

.LBB0_516:
	s_bitcmp1_b32 s19, 0
	s_cselect_b32 s2, 0x10400, 0
	v_or_b32_e32 v2, s2, v176
	v_add3_u32 v148, v2, v171, v169
	v_add3_u32 v2, v2, v170, v169
	ds_read_b128 v[132:135], v148 offset:33792
	ds_read_b128 v[136:139], v2
	ds_read_b128 v[140:143], v148 offset:35840
	ds_read_b128 v[144:147], v148 offset:37888
	ds_read_b128 v[148:151], v148 offset:39936
	v_lshrrev_b32_e32 v156, 2, v164
	s_waitcnt lgkmcnt(3)
	v_mfma_f32_16x16x32_bf16 v[128:131], v[132:135], v[136:139], v[128:131]
	s_waitcnt lgkmcnt(2)
	v_mfma_f32_16x16x32_bf16 v[124:127], v[140:143], v[136:139], v[124:127]
	s_waitcnt lgkmcnt(1)
	v_mfma_f32_16x16x32_bf16 v[120:123], v[144:147], v[136:139], v[120:123]
	s_waitcnt lgkmcnt(0)
	v_mfma_f32_16x16x32_bf16 v[116:119], v[148:151], v[136:139], v[116:119]
	ds_read_b128 v[136:139], v2 offset:2048
	s_waitcnt lgkmcnt(0)
	v_mfma_f32_16x16x32_bf16 v[112:115], v[132:135], v[136:139], v[112:115]
	v_mfma_f32_16x16x32_bf16 v[108:111], v[140:143], v[136:139], v[108:111]
	v_mfma_f32_16x16x32_bf16 v[104:107], v[144:147], v[136:139], v[104:107]
	v_mfma_f32_16x16x32_bf16 v[100:103], v[148:151], v[136:139], v[100:103]
	ds_read_b128 v[136:139], v2 offset:4096
	s_waitcnt lgkmcnt(0)
	v_mfma_f32_16x16x32_bf16 v[96:99], v[132:135], v[136:139], v[96:99]
	v_mfma_f32_16x16x32_bf16 v[92:95], v[140:143], v[136:139], v[92:95]
	v_mfma_f32_16x16x32_bf16 v[88:91], v[144:147], v[136:139], v[88:91]
	v_mfma_f32_16x16x32_bf16 v[84:87], v[148:151], v[136:139], v[84:87]
	ds_read_b128 v[136:139], v2 offset:6144
	s_waitcnt lgkmcnt(0)
	v_mfma_f32_16x16x32_bf16 v[80:83], v[132:135], v[136:139], v[80:83]
	v_mfma_f32_16x16x32_bf16 v[76:79], v[140:143], v[136:139], v[76:79]
	v_mfma_f32_16x16x32_bf16 v[72:75], v[144:147], v[136:139], v[72:75]
	v_mfma_f32_16x16x32_bf16 v[68:71], v[148:151], v[136:139], v[68:71]
	ds_read_b128 v[136:139], v2 offset:8192
	s_waitcnt lgkmcnt(0)
	v_mfma_f32_16x16x32_bf16 v[64:67], v[132:135], v[136:139], v[64:67]
	v_mfma_f32_16x16x32_bf16 v[60:63], v[140:143], v[136:139], v[60:63]
	v_mfma_f32_16x16x32_bf16 v[56:59], v[144:147], v[136:139], v[56:59]
	v_mfma_f32_16x16x32_bf16 v[52:55], v[148:151], v[136:139], v[52:55]
	ds_read_b128 v[136:139], v2 offset:10240
	s_waitcnt lgkmcnt(0)
	v_mfma_f32_16x16x32_bf16 v[48:51], v[132:135], v[136:139], v[48:51]
	v_mfma_f32_16x16x32_bf16 v[44:47], v[140:143], v[136:139], v[44:47]
	v_mfma_f32_16x16x32_bf16 v[40:43], v[144:147], v[136:139], v[40:43]
	v_mfma_f32_16x16x32_bf16 v[36:39], v[148:151], v[136:139], v[36:39]
	ds_read_b128 v[136:139], v2 offset:12288
	s_waitcnt lgkmcnt(0)
	v_mfma_f32_16x16x32_bf16 v[32:35], v[132:135], v[136:139], v[32:35]
	v_mfma_f32_16x16x32_bf16 v[28:31], v[140:143], v[136:139], v[28:31]
	v_mfma_f32_16x16x32_bf16 v[24:27], v[144:147], v[136:139], v[24:27]
	v_mfma_f32_16x16x32_bf16 v[20:23], v[148:151], v[136:139], v[20:23]
	ds_read_b128 v[136:139], v2 offset:14336
	v_or_b32_e32 v2, s2, v172
	v_add3_u32 v152, v2, v171, v169
	v_add3_u32 v2, v2, v170, v169
	s_waitcnt lgkmcnt(0)
	v_mfma_f32_16x16x32_bf16 v[16:19], v[132:135], v[136:139], v[16:19]
	ds_read_b128 v[132:135], v152 offset:33792
	v_mfma_f32_16x16x32_bf16 v[12:15], v[140:143], v[136:139], v[12:15]
	v_mfma_f32_16x16x32_bf16 v[8:11], v[144:147], v[136:139], v[8:11]
	v_mfma_f32_16x16x32_bf16 v[4:7], v[148:151], v[136:139], v[4:7]
	ds_read_b128 v[136:139], v152 offset:35840
	ds_read_b128 v[140:143], v2
	ds_read_b128 v[144:147], v2 offset:2048
	ds_read_b128 v[148:151], v152 offset:37888
	ds_read_b128 v[152:155], v152 offset:39936
	s_waitcnt lgkmcnt(3)
	v_mfma_f32_16x16x32_bf16 v[128:131], v[132:135], v[140:143], v[128:131]
	v_mfma_f32_16x16x32_bf16 v[124:127], v[136:139], v[140:143], v[124:127]
	s_waitcnt lgkmcnt(1)
	v_mfma_f32_16x16x32_bf16 v[120:123], v[148:151], v[140:143], v[120:123]
	s_waitcnt lgkmcnt(0)
	v_mfma_f32_16x16x32_bf16 v[116:119], v[152:155], v[140:143], v[116:119]
	v_mfma_f32_16x16x32_bf16 v[112:115], v[132:135], v[144:147], v[112:115]
	v_mfma_f32_16x16x32_bf16 v[108:111], v[136:139], v[144:147], v[108:111]
	v_mfma_f32_16x16x32_bf16 v[104:107], v[148:151], v[144:147], v[104:107]
	v_mfma_f32_16x16x32_bf16 v[100:103], v[152:155], v[144:147], v[100:103]
	ds_read_b128 v[140:143], v2 offset:4096
	ds_read_b128 v[144:147], v2 offset:6144
	s_waitcnt lgkmcnt(1)
	v_mfma_f32_16x16x32_bf16 v[96:99], v[132:135], v[140:143], v[96:99]
	v_mfma_f32_16x16x32_bf16 v[92:95], v[136:139], v[140:143], v[92:95]
	v_mfma_f32_16x16x32_bf16 v[88:91], v[148:151], v[140:143], v[88:91]
	v_mfma_f32_16x16x32_bf16 v[84:87], v[152:155], v[140:143], v[84:87]
	s_waitcnt lgkmcnt(0)
	v_mfma_f32_16x16x32_bf16 v[80:83], v[132:135], v[144:147], v[80:83]
	v_mfma_f32_16x16x32_bf16 v[76:79], v[136:139], v[144:147], v[76:79]
	v_mfma_f32_16x16x32_bf16 v[72:75], v[148:151], v[144:147], v[72:75]
	v_mfma_f32_16x16x32_bf16 v[68:71], v[152:155], v[144:147], v[68:71]
	ds_read_b128 v[140:143], v2 offset:8192
	ds_read_b128 v[144:147], v2 offset:10240
	s_waitcnt lgkmcnt(1)
	v_mfma_f32_16x16x32_bf16 v[64:67], v[132:135], v[140:143], v[64:67]
	v_mfma_f32_16x16x32_bf16 v[60:63], v[136:139], v[140:143], v[60:63]
	v_mfma_f32_16x16x32_bf16 v[56:59], v[148:151], v[140:143], v[56:59]
	v_mfma_f32_16x16x32_bf16 v[52:55], v[152:155], v[140:143], v[52:55]
	s_waitcnt lgkmcnt(0)
	v_mfma_f32_16x16x32_bf16 v[48:51], v[132:135], v[144:147], v[48:51]
	v_mfma_f32_16x16x32_bf16 v[44:47], v[136:139], v[144:147], v[44:47]
	v_mfma_f32_16x16x32_bf16 v[40:43], v[148:151], v[144:147], v[40:43]
	v_mfma_f32_16x16x32_bf16 v[36:39], v[152:155], v[144:147], v[36:39]
	ds_read_b128 v[140:143], v2 offset:12288
	ds_read_b128 v[144:147], v2 offset:14336
	v_lshlrev_b32_e32 v2, 6, v166
	s_waitcnt lgkmcnt(0)
	v_mfma_f32_16x16x32_bf16 v[32:35], v[132:135], v[140:143], v[32:35]
	s_barrier
	v_mfma_f32_16x16x32_bf16 v[28:31], v[136:139], v[140:143], v[28:31]
	v_mfma_f32_16x16x32_bf16 v[24:27], v[148:151], v[140:143], v[24:27]
	v_mfma_f32_16x16x32_bf16 v[20:23], v[152:155], v[140:143], v[20:23]
	v_and_b32_e32 v140, 12, v156
	v_add3_u32 v2, v140, s16, v2
	v_lshlrev_b32_e32 v140, 7, v165
	v_mfma_f32_16x16x32_bf16 v[16:19], v[132:135], v[144:147], v[16:19]
	v_and_b32_e32 v132, 15, v164
	v_add3_u32 v134, v132, s17, v140
	v_mad_u64_u32 v[132:133], s[2:3], v134, s18, 0
	v_ashrrev_i32_e32 v135, 31, v134
	v_mfma_f32_16x16x32_bf16 v[12:15], v[136:139], v[144:147], v[12:15]
	v_mov_b32_e32 v136, v133
	v_mad_u64_u32 v[136:137], s[2:3], v135, s18, v[136:137]
	v_mfma_f32_16x16x32_bf16 v[8:11], v[148:151], v[144:147], v[8:11]
	v_mov_b32_e32 v133, v136
	v_lshl_add_u64 v[132:133], v[132:133], 1, s[14:15]
	v_cmp_gt_u32_e32 vcc, s18, v2
	v_mfma_f32_16x16x32_bf16 v[4:7], v[152:155], v[144:147], v[4:7]
	s_cbranch_vccz .Lmla_st_done
	v_lshl_add_u64 v[132:133], v[2:3], 1, v[132:133]
	v_and_b32_e32 v140, 16, v164
	v_lshrrev_b32_e32 v141, 1, v140
	v_add_u32_e32 v140, v140, v141
	v_mov_b32_e32 v141, 0
	s_lshl_b32 s4, s18, 5
	s_mov_b32 s5, 0
	v_lshl_add_u64 v[132:133], v[140:141], 0, v[132:133]
	v_cvt_pk_bf16_f32 v127, v126, v127
	v_cvt_pk_bf16_f32 v126, v124, v125
	v_cvt_pk_bf16_f32 v124, v128, v129
	v_cvt_pk_bf16_f32 v125, v130, v131
	v_cvt_pk_bf16_f32 v119, v118, v119
	v_cvt_pk_bf16_f32 v118, v116, v117
	v_cvt_pk_bf16_f32 v116, v120, v121
	v_cvt_pk_bf16_f32 v117, v122, v123
	s_nop 1
	v_permlane16_swap_b32 v124, v126
	v_permlane16_swap_b32 v125, v127
	v_permlane16_swap_b32 v116, v118
	v_permlane16_swap_b32 v117, v119
	s_nop 1
	global_store_dwordx4 v[132:133], v[124:127], off sc1
	global_store_dwordx4 v[132:133], v[116:119], off offset:64 sc1
	v_lshl_add_u64 v[132:133], s[4:5], 0, v[132:133]
	v_cvt_pk_bf16_f32 v111, v110, v111
	v_cvt_pk_bf16_f32 v110, v108, v109
	v_cvt_pk_bf16_f32 v108, v112, v113
	v_cvt_pk_bf16_f32 v109, v114, v115
	v_cvt_pk_bf16_f32 v103, v102, v103
	v_cvt_pk_bf16_f32 v102, v100, v101
	v_cvt_pk_bf16_f32 v100, v104, v105
	v_cvt_pk_bf16_f32 v101, v106, v107
	s_nop 1
	v_permlane16_swap_b32 v108, v110
	v_permlane16_swap_b32 v109, v111
	v_permlane16_swap_b32 v100, v102
	v_permlane16_swap_b32 v101, v103
	s_nop 1
	global_store_dwordx4 v[132:133], v[108:111], off sc1
	global_store_dwordx4 v[132:133], v[100:103], off offset:64 sc1
	v_lshl_add_u64 v[132:133], s[4:5], 0, v[132:133]
	v_cvt_pk_bf16_f32 v95, v94, v95
	v_cvt_pk_bf16_f32 v94, v92, v93
	v_cvt_pk_bf16_f32 v92, v96, v97
	v_cvt_pk_bf16_f32 v93, v98, v99
	v_cvt_pk_bf16_f32 v87, v86, v87
	v_cvt_pk_bf16_f32 v86, v84, v85
	v_cvt_pk_bf16_f32 v84, v88, v89
	v_cvt_pk_bf16_f32 v85, v90, v91
	s_nop 1
	v_permlane16_swap_b32 v92, v94
	v_permlane16_swap_b32 v93, v95
	v_permlane16_swap_b32 v84, v86
	v_permlane16_swap_b32 v85, v87
	s_nop 1
	global_store_dwordx4 v[132:133], v[92:95], off sc1
	global_store_dwordx4 v[132:133], v[84:87], off offset:64 sc1
	v_lshl_add_u64 v[132:133], s[4:5], 0, v[132:133]
	v_cvt_pk_bf16_f32 v79, v78, v79
	v_cvt_pk_bf16_f32 v78, v76, v77
	v_cvt_pk_bf16_f32 v76, v80, v81
	v_cvt_pk_bf16_f32 v77, v82, v83
	v_cvt_pk_bf16_f32 v71, v70, v71
	v_cvt_pk_bf16_f32 v70, v68, v69
	v_cvt_pk_bf16_f32 v68, v72, v73
	v_cvt_pk_bf16_f32 v69, v74, v75
	s_nop 1
	v_permlane16_swap_b32 v76, v78
	v_permlane16_swap_b32 v77, v79
	v_permlane16_swap_b32 v68, v70
	v_permlane16_swap_b32 v69, v71
	s_nop 1
	global_store_dwordx4 v[132:133], v[76:79], off sc1
	global_store_dwordx4 v[132:133], v[68:71], off offset:64 sc1
	v_lshl_add_u64 v[132:133], s[4:5], 0, v[132:133]
	v_cvt_pk_bf16_f32 v63, v62, v63
	v_cvt_pk_bf16_f32 v62, v60, v61
	v_cvt_pk_bf16_f32 v60, v64, v65
	v_cvt_pk_bf16_f32 v61, v66, v67
	v_cvt_pk_bf16_f32 v55, v54, v55
	v_cvt_pk_bf16_f32 v54, v52, v53
	v_cvt_pk_bf16_f32 v52, v56, v57
	v_cvt_pk_bf16_f32 v53, v58, v59
	s_nop 1
	v_permlane16_swap_b32 v60, v62
	v_permlane16_swap_b32 v61, v63
	v_permlane16_swap_b32 v52, v54
	v_permlane16_swap_b32 v53, v55
	s_nop 1
	global_store_dwordx4 v[132:133], v[60:63], off sc1
	global_store_dwordx4 v[132:133], v[52:55], off offset:64 sc1
	v_lshl_add_u64 v[132:133], s[4:5], 0, v[132:133]
	v_cvt_pk_bf16_f32 v47, v46, v47
	v_cvt_pk_bf16_f32 v46, v44, v45
	v_cvt_pk_bf16_f32 v44, v48, v49
	v_cvt_pk_bf16_f32 v45, v50, v51
	v_cvt_pk_bf16_f32 v39, v38, v39
	v_cvt_pk_bf16_f32 v38, v36, v37
	v_cvt_pk_bf16_f32 v36, v40, v41
	v_cvt_pk_bf16_f32 v37, v42, v43
	s_nop 1
	v_permlane16_swap_b32 v44, v46
	v_permlane16_swap_b32 v45, v47
	v_permlane16_swap_b32 v36, v38
	v_permlane16_swap_b32 v37, v39
	s_nop 1
	global_store_dwordx4 v[132:133], v[44:47], off sc1
	global_store_dwordx4 v[132:133], v[36:39], off offset:64 sc1
	v_lshl_add_u64 v[132:133], s[4:5], 0, v[132:133]
	v_cvt_pk_bf16_f32 v31, v30, v31
	v_cvt_pk_bf16_f32 v30, v28, v29
	v_cvt_pk_bf16_f32 v28, v32, v33
	v_cvt_pk_bf16_f32 v29, v34, v35
	v_cvt_pk_bf16_f32 v23, v22, v23
	v_cvt_pk_bf16_f32 v22, v20, v21
	v_cvt_pk_bf16_f32 v20, v24, v25
	v_cvt_pk_bf16_f32 v21, v26, v27
	s_nop 1
	v_permlane16_swap_b32 v28, v30
	v_permlane16_swap_b32 v29, v31
	v_permlane16_swap_b32 v20, v22
	v_permlane16_swap_b32 v21, v23
	s_nop 1
	global_store_dwordx4 v[132:133], v[28:31], off sc1
	global_store_dwordx4 v[132:133], v[20:23], off offset:64 sc1
	v_lshl_add_u64 v[132:133], s[4:5], 0, v[132:133]
	v_cvt_pk_bf16_f32 v15, v14, v15
	v_cvt_pk_bf16_f32 v14, v12, v13
	v_cvt_pk_bf16_f32 v12, v16, v17
	v_cvt_pk_bf16_f32 v13, v18, v19
	v_cvt_pk_bf16_f32 v7, v6, v7
	v_cvt_pk_bf16_f32 v6, v4, v5
	v_cvt_pk_bf16_f32 v4, v8, v9
	v_cvt_pk_bf16_f32 v5, v10, v11
	s_nop 1
	v_permlane16_swap_b32 v12, v14
	v_permlane16_swap_b32 v13, v15
	v_permlane16_swap_b32 v4, v6
	v_permlane16_swap_b32 v5, v7
	s_nop 1
	global_store_dwordx4 v[132:133], v[12:15], off sc1
	global_store_dwordx4 v[132:133], v[4:7], off offset:64 sc1
